# A/B: nt hints on P0 / EpiResid once-read loads removed (default cache policy)
# speedup vs baseline: 1.0070x; 1.0008x over previous
; __device__ __forceinline__ unsigned pk2(float lo, float hi) { f32x2_t v = {lo, hi}; bf16x2_t b = __builtin_convertvector(v, bf16x2_t); return __builtin_bit_cast(unsigned, b); }
; __device__ __forceinline__ void rms_row2048(const float* xrow, const float* g, bf16_t* orow, int lane) {
;     const f32x4* xr = (const f32x4*)xrow + lane; const f32x4* gr = (const f32x4*)g + lane;
;     f32x4 v[8]; float s = 0.f;
; #pragma unroll
;     for (int j = 0; j < 8; ++j) { v[j] = xr[64 * j]; s += (v[j].x * v[j].x + v[j].y * v[j].y) + (v[j].z * v[j].z + v[j].w * v[j].w); }
;     const float r = rsqrtf(wave_sum(s) * (1.f / 2048.f) + EPS);
;     u32x2* o8 = (u32x2*)orow + lane;
; #pragma unroll
;     for (int j = 0; j < 8; ++j) { const f32x4 gg = gr[64 * j]; u32x2 w; w.x = pk2(v[j].x * r * gg.x, v[j].y * r * gg.y); w.y = pk2(v[j].z * r * gg.z, v[j].w * r * gg.w); o8[64 * j] = w; }
; __global__ void __launch_bounds__(512, 2) mega_fwd(Args args) {
;     ...
;         for (int m = gw; m < T; m += NGW) rms_row2048(x + (size_t)m * D, args.in[3], H + (size_t)m * D, lane);
.LBB0_257:
	s_or_b64 exec, exec, s[2:3]
	v_readlane_b32 s0, v238, 38
	s_cmpk_gt_i32 s0, 0x3fff
	v_readlane_b32 s1, v238, 39
	s_cbranch_scc1 .LBB0_260
	v_lshlrev_b32_e32 v0, 4, v184
	v_mov_b32_e32 v1, 0
	v_lshl_add_u64 v[16:17], s[58:59], 0, v[0:1]
	s_mov_b64 s[0:1], 0x1000
	v_lshl_add_u64 v[18:19], v[16:17], 0, s[0:1]
	s_mov_b64 s[0:1], 0x1400
	v_lshl_add_u64 v[20:21], v[16:17], 0, s[0:1]
	s_mov_b64 s[0:1], 0x1800
	v_lshl_add_u64 v[22:23], v[16:17], 0, s[0:1]
	v_readlane_b32 s0, v238, 38
	v_readlane_b32 s1, v238, 39
	s_mov_b32 s8, s0
	s_ashr_i32 s9, s0, 31
	s_lshl_b64 s[0:1], s[8:9], 12
	s_add_u32 s0, s86, s0
	v_lshlrev_b32_e32 v2, 3, v184
	v_mov_b32_e32 v3, v1
	s_addc_u32 s1, s87, s1
	v_lshl_add_u64 v[2:3], s[0:1], 0, v[2:3]
	s_mov_b64 s[0:1], 0x6800e00
	s_ashr_i32 s97, s96, 31
	v_lshl_add_u64 v[26:27], v[2:3], 0, s[0:1]
	s_lshl_b64 s[0:1], s[96:97], 12
	s_lshl_b64 s[4:5], s[8:9], 13
	s_add_u32 s4, s52, s4
	s_addc_u32 s5, s53, s5
	s_mov_b64 s[2:3], 0x1c00
	v_lshl_add_u64 v[0:1], s[4:5], 0, v[0:1]
	s_mov_b32 s6, s8
	v_lshl_add_u64 v[24:25], v[16:17], 0, s[2:3]
	v_lshl_add_u64 v[28:29], v[0:1], 0, s[2:3]
	s_lshl_b64 s[2:3], s[96:97], 13
	v_mov_b32_e32 v30, 0x358637bd
	s_mov_b32 s4, 0x800000
	v_writelane_b32 v238, s6, 38
	s_mov_b32 s5, s8
	s_nop 0
	v_writelane_b32 v238, s7, 39
	global_load_dwordx4 v[80:83], v[16:17], off
	global_load_dwordx4 v[84:87], v[16:17], off offset:1024
	global_load_dwordx4 v[88:91], v[16:17], off offset:2048
	global_load_dwordx4 v[92:95], v[16:17], off offset:3072
	global_load_dwordx4 v[96:99], v[18:19], off
	global_load_dwordx4 v[100:103], v[20:21], off
	global_load_dwordx4 v[104:107], v[22:23], off
	global_load_dwordx4 v[108:111], v[24:25], off
	v_add_co_u32_e32 v144, vcc, 0xfffff000, v28
	global_load_dwordx4 v[112:115], v[28:29], off offset:-3072
	global_load_dwordx4 v[116:119], v[28:29], off offset:-2048
	global_load_dwordx4 v[120:123], v[28:29], off offset:-1024
	v_addc_co_u32_e32 v145, vcc, -1, v29, vcc
	global_load_dwordx4 v[124:127], v[144:145], off offset:-3072
	global_load_dwordx4 v[128:131], v[144:145], off offset:-2048
	global_load_dwordx4 v[132:135], v[144:145], off offset:-1024
	global_load_dwordx4 v[136:139], v[28:29], off offset:-4096
	s_nop 0
	global_load_dwordx4 v[140:143], v[28:29], off
	s_add_i32 s5, s5, s96
	s_cmpk_lt_i32 s5, 0x4000
	v_lshl_add_u64 v[28:29], v[28:29], 0, s[2:3]
	s_cselect_b32 s16, 1, 0
	s_waitcnt vmcnt(0)
	v_and_b32_e32 v244, 1, v184
	v_lshrrev_b32_e32 v245, 1, v184
	v_lshlrev_b32_e32 v244, 9, v244
	v_lshl_add_u32 v244, v245, 4, v244
	v_lshlrev_b32_e32 v245, 3, v184
	v_sub_u32_e32 v244, v244, v245
	v_ashrrev_i32_e32 v245, 31, v244
	v_lshl_add_u64 v[26:27], v[26:27], 0, v[244:245]
	s_mov_b32 s12, 0xaaaaaaaa
	s_mov_b32 s13, 0xaaaaaaaa

; __device__ __forceinline__ unsigned pk2(float lo, float hi) { f32x2_t v = {lo, hi}; bf16x2_t b = __builtin_convertvector(v, bf16x2_t); return __builtin_bit_cast(unsigned, b); }
; __device__ __forceinline__ float xor16_sum(float v) { float a = v, b = v; swap16(a, b); return a + b; }
; __device__ __forceinline__ float xor32_sum(float v) { float a = v, b = v; swap32(a, b); return a + b; }
;     __device__ __forceinline__ void operator()(const f32x4 (&acc)[2][2][4][2], const Unit& u, int wr, int wc, int fr, int fq) const {
;         const int row0 = u.pm * BM + wr * 64 + fr; constexpr int ldc = 2048; constexpr float alpha = 0.5f * ALPHA2;
;         bf16_t* const xb = (bf16_t*)(ws + XBOFF); __attribute__((address_space(1))) float* const ss = (__attribute__((address_space(1))) float*)(ws + SSOFF);
; #pragma unroll
;         for (int ai = 0; ai < 2; ++ai)
; #pragma unroll
;             for (int m = 0; m < 4; ++m) {
;                 const int row = row0 + ai * HALF + m * 16; float sq = 0.f;
; #pragma unroll
;                 for (int bj = 0; bj < 2; ++bj)
; #pragma unroll
;                     for (int n = 0; n < 2; ++n) {
;                         const size_t idx = (size_t)row * ldc + u.pn * BM + bj * HALF + wc * 32 + 8 * fq + 4 * n;
;                         const f32x4 b = *(const f32x4*)(base + idx);
;                         const f32x4 v = b + acc[ai][bj][m][n] * alpha;
;                         *(f32x4*)(out + idx) = v;
;                         if (NORM) { u32x2 w; w.x = pk2(v[0], v[1]); w.y = pk2(v[2], v[3]); *(u32x2*)(xb + idx) = w; sq += (v[0] * v[0] + v[1] * v[1]) + (v[2] * v[2] + v[3] * v[3]); }
;                     }
;                 if (NORM) { sq = xor16_sum(sq); sq = xor32_sum(sq); if (fq == 0) __hip_atomic_fetch_add(ss + row, sq, __ATOMIC_RELAXED, __HIP_MEMORY_SCOPE_AGENT); }
;             }
.LBB0_423:
	v_lshl_add_u32 v148, s14, 8, v137
	s_lshl_b32 s12, s16, 8
	s_ashr_i32 s13, s12, 31
	v_ashrrev_i32_e32 v149, 31, v148
	v_mov_b32_e32 v147, s13
	v_or_b32_e32 v146, s12, v136
	v_lshlrev_b64 v[154:155], 11, v[148:149]
	v_lshl_add_u64 v[158:159], v[154:155], 0, v[146:147]
	v_lshlrev_b64 v[160:161], 2, v[158:159]
	v_lshl_add_u64 v[162:163], s[52:53], 0, v[160:161]
	v_mov_b32_e32 v232, v162
	v_mov_b32_e32 v233, v163
	v_mov_b32_e32 v231, 0
	v_mov_b32_e32 v230, 0x0
	v_lshl_add_u64 v[228:229], v[232:233], 0, v[230:231]
	global_load_dwordx4 v[164:167], v[228:229], off
	global_load_dwordx4 v[168:171], v[228:229], off offset:16
	global_load_dwordx4 v[172:175], v[228:229], off offset:512
	global_load_dwordx4 v[176:179], v[228:229], off offset:528
	v_mov_b32_e32 v230, 0x20000
	v_lshl_add_u64 v[228:229], v[232:233], 0, v[230:231]
	global_load_dwordx4 v[180:183], v[228:229], off
	global_load_dwordx4 v[188:191], v[228:229], off offset:16
	global_load_dwordx4 v[192:195], v[228:229], off offset:512
	global_load_dwordx4 v[196:199], v[228:229], off offset:528
	v_mov_b32_e32 v230, 0x40000
	v_lshl_add_u64 v[228:229], v[232:233], 0, v[230:231]
	global_load_dwordx4 v[200:203], v[228:229], off
	global_load_dwordx4 v[204:207], v[228:229], off offset:16
	global_load_dwordx4 v[208:211], v[228:229], off offset:512
	global_load_dwordx4 v[212:215], v[228:229], off offset:528
	v_mov_b32_e32 v230, 0x60000
	v_lshl_add_u64 v[228:229], v[232:233], 0, v[230:231]
	global_load_dwordx4 v[216:219], v[228:229], off
	global_load_dwordx4 v[220:223], v[228:229], off offset:16
	global_load_dwordx4 v[224:227], v[228:229], off offset:512
	global_load_dwordx4 v[234:237], v[228:229], off offset:528
	s_nop 0
	v_lshlrev_b64 v[158:159], 1, v[158:159]
	s_nop 0
	s_waitcnt vmcnt(12)
	v_pk_fma_f32 v[126:127], v[126:127], 0.5, v[166:167] op_sel_hi:[1,0,1]
	v_pk_fma_f32 v[124:125], v[124:125], 0.5, v[164:165] op_sel_hi:[1,0,1]
	v_lshl_add_u64 v[154:155], s[30:31], 0, v[160:161]
	global_store_dwordx4 v[154:155], v[124:127], off
	v_cvt_pk_bf16_f32 v240, v124, v125
	v_cvt_pk_bf16_f32 v241, v126, v127
	v_mul_f32_e32 v125, v125, v125
	v_lshl_add_u64 v[160:161], s[40:41], 0, v[158:159]
	v_fmac_f32_e32 v125, v124, v124
	v_mul_f32_e32 v124, v127, v127
	s_nop 0
	v_fmac_f32_e32 v124, v126, v126
	v_add_f32_e32 v156, v125, v124
	s_nop 0
	s_nop 0
	v_pk_fma_f32 v[122:123], v[122:123], 0.5, v[170:171] op_sel_hi:[1,0,1]
	v_pk_fma_f32 v[120:121], v[120:121], 0.5, v[168:169] op_sel_hi:[1,0,1]
	global_store_dwordx4 v[154:155], v[120:123], off offset:16
	v_cvt_pk_bf16_f32 v242, v120, v121
	v_or_b32_e32 v126, 8, v158
	v_mul_f32_e32 v121, v121, v121
	v_mov_b32_e32 v127, v159
	v_fmac_f32_e32 v121, v120, v120
	v_mul_f32_e32 v120, v123, v123
	v_cvt_pk_bf16_f32 v243, v122, v123
	v_lshl_add_u64 v[126:127], s[40:41], 0, v[126:127]
	v_fmac_f32_e32 v120, v122, v122
	global_store_dwordx4 v[126:127], v[240:243], off offset:-8
	v_add_f32_e32 v120, v121, v120
	v_add_f32_e32 v124, v156, v120
	s_nop 0
	s_nop 0
	v_pk_fma_f32 v[118:119], v[118:119], 0.5, v[174:175] op_sel_hi:[1,0,1]
	v_pk_fma_f32 v[116:117], v[116:117], 0.5, v[172:173] op_sel_hi:[1,0,1]
	global_store_dwordx4 v[154:155], v[116:119], off offset:512
	v_cvt_pk_bf16_f32 v240, v116, v117
	v_or_b32_e32 v122, 0x100, v158
	v_mul_f32_e32 v117, v117, v117
	v_mov_b32_e32 v123, v159
	v_fmac_f32_e32 v117, v116, v116
	v_mul_f32_e32 v116, v119, v119
	v_cvt_pk_bf16_f32 v241, v118, v119
	v_lshl_add_u64 v[122:123], s[40:41], 0, v[122:123]
	v_fmac_f32_e32 v116, v118, v118
	s_nop 0
	v_add_f32_e32 v116, v117, v116
	v_add_f32_e32 v120, v124, v116
	s_nop 0
	v_or_b32_e32 v158, 0x108, v158
	s_nop 0
	v_pk_fma_f32 v[114:115], v[114:115], 0.5, v[178:179] op_sel_hi:[1,0,1]
	v_pk_fma_f32 v[112:113], v[112:113], 0.5, v[176:177] op_sel_hi:[1,0,1]
	v_mov_b32_e32 v230, 0x100000
	v_lshl_add_u64 v[228:229], v[232:233], 0, v[230:231]
	global_load_dwordx4 v[164:167], v[228:229], off
	global_load_dwordx4 v[168:171], v[228:229], off offset:16
	global_load_dwordx4 v[172:175], v[228:229], off offset:512
	global_load_dwordx4 v[176:179], v[228:229], off offset:528
	global_store_dwordx4 v[154:155], v[112:115], off offset:528
	v_cvt_pk_bf16_f32 v242, v112, v113
	v_cvt_pk_bf16_f32 v243, v114, v115
	v_mul_f32_e32 v113, v113, v113
	v_fmac_f32_e32 v113, v112, v112
	v_mul_f32_e32 v112, v115, v115
	v_fmac_f32_e32 v112, v114, v114
	v_add_f32_e32 v112, v113, v112
	v_add_f32_e32 v112, v120, v112
	v_mov_b32_e32 v113, v112
	s_nop 1
	v_permlane16_swap_b32 v112, v113
	v_lshl_add_u64 v[118:119], s[40:41], 0, v[158:159]
	v_add_f32_e32 v112, v112, v113
	v_mov_b32_e32 v113, v112
	global_store_dwordx4 v[118:119], v[240:243], off offset:-8
	s_nop 1
	v_permlane32_swap_b32 v112, v113
	s_and_saveexec_b64 s[12:13], s[2:3]
	s_cbranch_execz .LBB0_425
	v_lshl_add_u64 v[114:115], v[148:149], 2, s[90:91]
	v_add_f32_e32 v112, v112, v113
	global_atomic_add_f32 v[114:115], v112, off
; __device__ __forceinline__ unsigned pk2(float lo, float hi) { f32x2_t v = {lo, hi}; bf16x2_t b = __builtin_convertvector(v, bf16x2_t); return __builtin_bit_cast(unsigned, b); }
; __device__ __forceinline__ float xor16_sum(float v) { float a = v, b = v; swap16(a, b); return a + b; }
; __device__ __forceinline__ float xor32_sum(float v) { float a = v, b = v; swap32(a, b); return a + b; }
;     __device__ __forceinline__ void operator()(const f32x4 (&acc)[2][2][4][2], const Unit& u, int wr, int wc, int fr, int fq) const {
;         const int row0 = u.pm * BM + wr * 64 + fr; constexpr int ldc = 2048; constexpr float alpha = 0.5f * ALPHA2;
;         bf16_t* const xb = (bf16_t*)(ws + XBOFF); __attribute__((address_space(1))) float* const ss = (__attribute__((address_space(1))) float*)(ws + SSOFF);
; #pragma unroll
;         for (int ai = 0; ai < 2; ++ai)
; #pragma unroll
;             for (int m = 0; m < 4; ++m) {
;                 const int row = row0 + ai * HALF + m * 16; float sq = 0.f;
; #pragma unroll
;                 for (int bj = 0; bj < 2; ++bj)
; #pragma unroll
;                     for (int n = 0; n < 2; ++n) {
;                         const size_t idx = (size_t)row * ldc + u.pn * BM + bj * HALF + wc * 32 + 8 * fq + 4 * n;
;                         const f32x4 b = *(const f32x4*)(base + idx);
;                         const f32x4 v = b + acc[ai][bj][m][n] * alpha;
;                         *(f32x4*)(out + idx) = v;
;                         if (NORM) { u32x2 w; w.x = pk2(v[0], v[1]); w.y = pk2(v[2], v[3]); *(u32x2*)(xb + idx) = w; sq += (v[0] * v[0] + v[1] * v[1]) + (v[2] * v[2] + v[3] * v[3]); }
;                     }
;                 if (NORM) { sq = xor16_sum(sq); sq = xor32_sum(sq); if (fq == 0) __hip_atomic_fetch_add(ss + row, sq, __ATOMIC_RELAXED, __HIP_MEMORY_SCOPE_AGENT); }
;             }
.LBB0_425:
	s_or_b64 exec, exec, s[12:13]
	v_or_b32_e32 v112, 16, v148
	v_ashrrev_i32_e32 v113, 31, v112
	v_lshlrev_b64 v[114:115], 11, v[112:113]
	v_lshl_add_u64 v[118:119], v[114:115], 0, v[146:147]
	v_lshlrev_b64 v[120:121], 2, v[118:119]
	v_lshl_add_u64 v[122:123], s[52:53], 0, v[120:121]
	s_nop 0
	v_lshlrev_b64 v[118:119], 1, v[118:119]
	s_nop 0
	s_waitcnt vmcnt(18)
	v_pk_fma_f32 v[110:111], v[110:111], 0.5, v[182:183] op_sel_hi:[1,0,1]
	v_pk_fma_f32 v[108:109], v[108:109], 0.5, v[180:181] op_sel_hi:[1,0,1]
	v_lshl_add_u64 v[114:115], s[30:31], 0, v[120:121]
	global_store_dwordx4 v[114:115], v[108:111], off
	v_cvt_pk_bf16_f32 v240, v108, v109
	v_cvt_pk_bf16_f32 v241, v110, v111
	v_mul_f32_e32 v109, v109, v109
	v_lshl_add_u64 v[120:121], s[40:41], 0, v[118:119]
	v_fmac_f32_e32 v109, v108, v108
	v_mul_f32_e32 v108, v111, v111
	s_nop 0
	v_fmac_f32_e32 v108, v110, v110
	v_add_f32_e32 v116, v109, v108
	s_nop 0
	s_nop 0
	v_pk_fma_f32 v[106:107], v[106:107], 0.5, v[190:191] op_sel_hi:[1,0,1]
	v_pk_fma_f32 v[104:105], v[104:105], 0.5, v[188:189] op_sel_hi:[1,0,1]
	global_store_dwordx4 v[114:115], v[104:107], off offset:16
	v_cvt_pk_bf16_f32 v242, v104, v105
	v_or_b32_e32 v110, 8, v118
	v_mul_f32_e32 v105, v105, v105
	v_mov_b32_e32 v111, v119
	v_fmac_f32_e32 v105, v104, v104
	v_mul_f32_e32 v104, v107, v107
	v_cvt_pk_bf16_f32 v243, v106, v107
	v_lshl_add_u64 v[110:111], s[40:41], 0, v[110:111]
	v_fmac_f32_e32 v104, v106, v106
	global_store_dwordx4 v[110:111], v[240:243], off offset:-8
	v_add_f32_e32 v104, v105, v104
	v_add_f32_e32 v108, v116, v104
	s_nop 0
	s_nop 0
	v_pk_fma_f32 v[102:103], v[102:103], 0.5, v[194:195] op_sel_hi:[1,0,1]
	v_pk_fma_f32 v[100:101], v[100:101], 0.5, v[192:193] op_sel_hi:[1,0,1]
	global_store_dwordx4 v[114:115], v[100:103], off offset:512
	v_cvt_pk_bf16_f32 v240, v100, v101
	v_or_b32_e32 v106, 0x100, v118
	v_mul_f32_e32 v101, v101, v101
	v_mov_b32_e32 v107, v119
	v_fmac_f32_e32 v101, v100, v100
	v_mul_f32_e32 v100, v103, v103
	v_cvt_pk_bf16_f32 v241, v102, v103
	v_lshl_add_u64 v[106:107], s[40:41], 0, v[106:107]
	v_fmac_f32_e32 v100, v102, v102
	s_nop 0
	v_add_f32_e32 v100, v101, v100
	v_add_f32_e32 v104, v108, v100
	s_nop 0
	v_or_b32_e32 v118, 0x108, v118
	s_nop 0
	v_pk_fma_f32 v[98:99], v[98:99], 0.5, v[198:199] op_sel_hi:[1,0,1]
	v_pk_fma_f32 v[96:97], v[96:97], 0.5, v[196:197] op_sel_hi:[1,0,1]
	v_mov_b32_e32 v230, 0x120000
	v_lshl_add_u64 v[228:229], v[232:233], 0, v[230:231]
	global_load_dwordx4 v[180:183], v[228:229], off
	global_load_dwordx4 v[188:191], v[228:229], off offset:16
	global_load_dwordx4 v[192:195], v[228:229], off offset:512
	global_load_dwordx4 v[196:199], v[228:229], off offset:528
	global_store_dwordx4 v[114:115], v[96:99], off offset:528
	v_cvt_pk_bf16_f32 v242, v96, v97
	v_cvt_pk_bf16_f32 v243, v98, v99
	v_mul_f32_e32 v97, v97, v97
	v_fmac_f32_e32 v97, v96, v96
	v_mul_f32_e32 v96, v99, v99
	v_fmac_f32_e32 v96, v98, v98
	v_add_f32_e32 v96, v97, v96
	v_add_f32_e32 v96, v104, v96
	v_mov_b32_e32 v97, v96
	s_nop 1
	v_permlane16_swap_b32 v96, v97
	v_lshl_add_u64 v[102:103], s[40:41], 0, v[118:119]
	v_add_f32_e32 v96, v96, v97
	v_mov_b32_e32 v97, v96
	global_store_dwordx4 v[102:103], v[240:243], off offset:-8
	s_nop 1
	v_permlane32_swap_b32 v96, v97
	s_and_saveexec_b64 s[12:13], s[2:3]
	s_cbranch_execz .LBB0_427
	v_lshl_add_u64 v[98:99], v[112:113], 2, s[90:91]
	v_add_f32_e32 v96, v96, v97
	global_atomic_add_f32 v[98:99], v96, off
; __device__ __forceinline__ unsigned pk2(float lo, float hi) { f32x2_t v = {lo, hi}; bf16x2_t b = __builtin_convertvector(v, bf16x2_t); return __builtin_bit_cast(unsigned, b); }
; __device__ __forceinline__ float xor16_sum(float v) { float a = v, b = v; swap16(a, b); return a + b; }
; __device__ __forceinline__ float xor32_sum(float v) { float a = v, b = v; swap32(a, b); return a + b; }
;     __device__ __forceinline__ void operator()(const f32x4 (&acc)[2][2][4][2], const Unit& u, int wr, int wc, int fr, int fq) const {
;         const int row0 = u.pm * BM + wr * 64 + fr; constexpr int ldc = 2048; constexpr float alpha = 0.5f * ALPHA2;
;         bf16_t* const xb = (bf16_t*)(ws + XBOFF); __attribute__((address_space(1))) float* const ss = (__attribute__((address_space(1))) float*)(ws + SSOFF);
; #pragma unroll
;         for (int ai = 0; ai < 2; ++ai)
; #pragma unroll
;             for (int m = 0; m < 4; ++m) {
;                 const int row = row0 + ai * HALF + m * 16; float sq = 0.f;
; #pragma unroll
;                 for (int bj = 0; bj < 2; ++bj)
; #pragma unroll
;                     for (int n = 0; n < 2; ++n) {
;                         const size_t idx = (size_t)row * ldc + u.pn * BM + bj * HALF + wc * 32 + 8 * fq + 4 * n;
;                         const f32x4 b = *(const f32x4*)(base + idx);
;                         const f32x4 v = b + acc[ai][bj][m][n] * alpha;
;                         *(f32x4*)(out + idx) = v;
;                         if (NORM) { u32x2 w; w.x = pk2(v[0], v[1]); w.y = pk2(v[2], v[3]); *(u32x2*)(xb + idx) = w; sq += (v[0] * v[0] + v[1] * v[1]) + (v[2] * v[2] + v[3] * v[3]); }
;                     }
;                 if (NORM) { sq = xor16_sum(sq); sq = xor32_sum(sq); if (fq == 0) __hip_atomic_fetch_add(ss + row, sq, __ATOMIC_RELAXED, __HIP_MEMORY_SCOPE_AGENT); }
;             }
.LBB0_427:
	s_or_b64 exec, exec, s[12:13]
	v_or_b32_e32 v96, 32, v148
	v_ashrrev_i32_e32 v97, 31, v96
	v_lshlrev_b64 v[98:99], 11, v[96:97]
	v_lshl_add_u64 v[102:103], v[98:99], 0, v[146:147]
	v_lshlrev_b64 v[104:105], 2, v[102:103]
	v_lshl_add_u64 v[106:107], s[52:53], 0, v[104:105]
	s_nop 0
	v_lshlrev_b64 v[102:103], 1, v[102:103]
	s_nop 0
	s_waitcnt vmcnt(24)
	v_pk_fma_f32 v[94:95], v[94:95], 0.5, v[202:203] op_sel_hi:[1,0,1]
	v_pk_fma_f32 v[92:93], v[92:93], 0.5, v[200:201] op_sel_hi:[1,0,1]
	v_lshl_add_u64 v[98:99], s[30:31], 0, v[104:105]
	global_store_dwordx4 v[98:99], v[92:95], off
	v_cvt_pk_bf16_f32 v240, v92, v93
	v_cvt_pk_bf16_f32 v241, v94, v95
	v_mul_f32_e32 v93, v93, v93
	v_lshl_add_u64 v[104:105], s[40:41], 0, v[102:103]
	v_fmac_f32_e32 v93, v92, v92
	v_mul_f32_e32 v92, v95, v95
	s_nop 0
	v_fmac_f32_e32 v92, v94, v94
	v_add_f32_e32 v100, v93, v92
	s_nop 0
	s_nop 0
	v_pk_fma_f32 v[90:91], v[90:91], 0.5, v[206:207] op_sel_hi:[1,0,1]
	v_pk_fma_f32 v[88:89], v[88:89], 0.5, v[204:205] op_sel_hi:[1,0,1]
	global_store_dwordx4 v[98:99], v[88:91], off offset:16
	v_cvt_pk_bf16_f32 v242, v88, v89
	v_or_b32_e32 v94, 8, v102
	v_mul_f32_e32 v89, v89, v89
	v_mov_b32_e32 v95, v103
	v_fmac_f32_e32 v89, v88, v88
	v_mul_f32_e32 v88, v91, v91
	v_cvt_pk_bf16_f32 v243, v90, v91
	v_lshl_add_u64 v[94:95], s[40:41], 0, v[94:95]
	v_fmac_f32_e32 v88, v90, v90
	global_store_dwordx4 v[94:95], v[240:243], off offset:-8
	v_add_f32_e32 v88, v89, v88
	v_add_f32_e32 v92, v100, v88
	s_nop 0
	s_nop 0
	v_pk_fma_f32 v[86:87], v[86:87], 0.5, v[210:211] op_sel_hi:[1,0,1]
	v_pk_fma_f32 v[84:85], v[84:85], 0.5, v[208:209] op_sel_hi:[1,0,1]
	global_store_dwordx4 v[98:99], v[84:87], off offset:512
	v_cvt_pk_bf16_f32 v240, v84, v85
	v_or_b32_e32 v90, 0x100, v102
	v_mul_f32_e32 v85, v85, v85
	v_mov_b32_e32 v91, v103
	v_fmac_f32_e32 v85, v84, v84
	v_mul_f32_e32 v84, v87, v87
	v_cvt_pk_bf16_f32 v241, v86, v87
	v_lshl_add_u64 v[90:91], s[40:41], 0, v[90:91]
	v_fmac_f32_e32 v84, v86, v86
	s_nop 0
	v_add_f32_e32 v84, v85, v84
	v_add_f32_e32 v88, v92, v84
	s_nop 0
	v_or_b32_e32 v102, 0x108, v102
	s_nop 0
	v_pk_fma_f32 v[82:83], v[82:83], 0.5, v[214:215] op_sel_hi:[1,0,1]
	v_pk_fma_f32 v[80:81], v[80:81], 0.5, v[212:213] op_sel_hi:[1,0,1]
	v_mov_b32_e32 v230, 0x140000
	v_lshl_add_u64 v[228:229], v[232:233], 0, v[230:231]
	global_load_dwordx4 v[200:203], v[228:229], off
	global_load_dwordx4 v[204:207], v[228:229], off offset:16
	global_load_dwordx4 v[208:211], v[228:229], off offset:512
	global_load_dwordx4 v[212:215], v[228:229], off offset:528
	global_store_dwordx4 v[98:99], v[80:83], off offset:528
	v_cvt_pk_bf16_f32 v242, v80, v81
	v_cvt_pk_bf16_f32 v243, v82, v83
	v_mul_f32_e32 v81, v81, v81
	v_fmac_f32_e32 v81, v80, v80
	v_mul_f32_e32 v80, v83, v83
	v_fmac_f32_e32 v80, v82, v82
	v_add_f32_e32 v80, v81, v80
	v_add_f32_e32 v80, v88, v80
	v_mov_b32_e32 v81, v80
	s_nop 1
	v_permlane16_swap_b32 v80, v81
	v_lshl_add_u64 v[86:87], s[40:41], 0, v[102:103]
	v_add_f32_e32 v80, v80, v81
	v_mov_b32_e32 v81, v80
	global_store_dwordx4 v[86:87], v[240:243], off offset:-8
	s_nop 1
	v_permlane32_swap_b32 v80, v81
	s_and_saveexec_b64 s[12:13], s[2:3]
	s_cbranch_execz .LBB0_429
	v_lshl_add_u64 v[82:83], v[96:97], 2, s[90:91]
	v_add_f32_e32 v80, v80, v81
	global_atomic_add_f32 v[82:83], v80, off
.LBB0_429:
	s_or_b64 exec, exec, s[12:13]
	v_or_b32_e32 v80, 48, v148
	v_ashrrev_i32_e32 v81, 31, v80
	v_lshlrev_b64 v[82:83], 11, v[80:81]
	v_lshl_add_u64 v[86:87], v[82:83], 0, v[146:147]
	v_lshlrev_b64 v[88:89], 2, v[86:87]
	v_lshl_add_u64 v[90:91], s[52:53], 0, v[88:89]
	s_nop 0
	v_lshlrev_b64 v[86:87], 1, v[86:87]
	s_nop 0
	s_waitcnt vmcnt(30)
	v_pk_fma_f32 v[78:79], v[78:79], 0.5, v[218:219] op_sel_hi:[1,0,1]
	v_pk_fma_f32 v[76:77], v[76:77], 0.5, v[216:217] op_sel_hi:[1,0,1]
	v_lshl_add_u64 v[82:83], s[30:31], 0, v[88:89]
	global_store_dwordx4 v[82:83], v[76:79], off
	v_cvt_pk_bf16_f32 v240, v76, v77
	v_cvt_pk_bf16_f32 v241, v78, v79
	v_mul_f32_e32 v77, v77, v77
	v_lshl_add_u64 v[88:89], s[40:41], 0, v[86:87]
	v_fmac_f32_e32 v77, v76, v76
	v_mul_f32_e32 v76, v79, v79
	s_nop 0
	v_fmac_f32_e32 v76, v78, v78
	v_add_f32_e32 v84, v77, v76
	s_nop 0
	s_nop 0
	v_pk_fma_f32 v[74:75], v[74:75], 0.5, v[222:223] op_sel_hi:[1,0,1]
	v_pk_fma_f32 v[72:73], v[72:73], 0.5, v[220:221] op_sel_hi:[1,0,1]
	global_store_dwordx4 v[82:83], v[72:75], off offset:16
	v_cvt_pk_bf16_f32 v242, v72, v73
	v_or_b32_e32 v78, 8, v86
	v_mul_f32_e32 v73, v73, v73
	v_mov_b32_e32 v79, v87
	v_fmac_f32_e32 v73, v72, v72
	v_mul_f32_e32 v72, v75, v75
	v_cvt_pk_bf16_f32 v243, v74, v75
	v_lshl_add_u64 v[78:79], s[40:41], 0, v[78:79]
	v_fmac_f32_e32 v72, v74, v74
	global_store_dwordx4 v[78:79], v[240:243], off offset:-8
	v_add_f32_e32 v72, v73, v72
	v_add_f32_e32 v76, v84, v72
	s_nop 0
	s_nop 0
	v_pk_fma_f32 v[70:71], v[70:71], 0.5, v[226:227] op_sel_hi:[1,0,1]
	v_pk_fma_f32 v[68:69], v[68:69], 0.5, v[224:225] op_sel_hi:[1,0,1]
	global_store_dwordx4 v[82:83], v[68:71], off offset:512
	v_cvt_pk_bf16_f32 v240, v68, v69
	v_or_b32_e32 v74, 0x100, v86
	v_mul_f32_e32 v69, v69, v69
	v_mov_b32_e32 v75, v87
	v_fmac_f32_e32 v69, v68, v68
	v_mul_f32_e32 v68, v71, v71
	v_cvt_pk_bf16_f32 v241, v70, v71
	v_lshl_add_u64 v[74:75], s[40:41], 0, v[74:75]
	v_fmac_f32_e32 v68, v70, v70
	s_nop 0
	v_add_f32_e32 v68, v69, v68
	v_add_f32_e32 v72, v76, v68
	s_nop 0
	v_or_b32_e32 v86, 0x108, v86
	s_nop 0
	v_pk_fma_f32 v[66:67], v[66:67], 0.5, v[236:237] op_sel_hi:[1,0,1]
	v_pk_fma_f32 v[64:65], v[64:65], 0.5, v[234:235] op_sel_hi:[1,0,1]
	v_mov_b32_e32 v230, 0x160000
	v_lshl_add_u64 v[228:229], v[232:233], 0, v[230:231]
	global_load_dwordx4 v[216:219], v[228:229], off
	global_load_dwordx4 v[220:223], v[228:229], off offset:16
	global_load_dwordx4 v[224:227], v[228:229], off offset:512
	global_load_dwordx4 v[234:237], v[228:229], off offset:528
	global_store_dwordx4 v[82:83], v[64:67], off offset:528
	v_cvt_pk_bf16_f32 v242, v64, v65
	v_cvt_pk_bf16_f32 v243, v66, v67
	v_mul_f32_e32 v65, v65, v65
	v_fmac_f32_e32 v65, v64, v64
	v_mul_f32_e32 v64, v67, v67
	v_fmac_f32_e32 v64, v66, v66
	v_add_f32_e32 v64, v65, v64
	v_add_f32_e32 v64, v72, v64
	v_mov_b32_e32 v65, v64
	s_nop 1
	v_permlane16_swap_b32 v64, v65
	v_lshl_add_u64 v[70:71], s[40:41], 0, v[86:87]
	v_add_f32_e32 v64, v64, v65
	v_mov_b32_e32 v65, v64
	global_store_dwordx4 v[70:71], v[240:243], off offset:-8
	s_nop 1
	v_permlane32_swap_b32 v64, v65
	s_and_saveexec_b64 s[12:13], s[2:3]
	s_cbranch_execz .LBB0_431
	v_lshl_add_u64 v[66:67], v[80:81], 2, s[90:91]
	v_add_f32_e32 v64, v64, v65
	global_atomic_add_f32 v[66:67], v64, off

; __device__ __forceinline__ unsigned pk2(float lo, float hi) { f32x2_t v = {lo, hi}; bf16x2_t b = __builtin_convertvector(v, bf16x2_t); return __builtin_bit_cast(unsigned, b); }
; __device__ __forceinline__ float xor16_sum(float v) { float a = v, b = v; swap16(a, b); return a + b; }
; __device__ __forceinline__ float xor32_sum(float v) { float a = v, b = v; swap32(a, b); return a + b; }
;     __device__ __forceinline__ void operator()(const f32x4 (&acc)[2][2][4][2], const Unit& u, int wr, int wc, int fr, int fq) const {
;         const int row0 = u.pm * BM + wr * 64 + fr; constexpr int ldc = 2048; constexpr float alpha = 0.5f * ALPHA2;
;         bf16_t* const xb = (bf16_t*)(ws + XBOFF); __attribute__((address_space(1))) float* const ss = (__attribute__((address_space(1))) float*)(ws + SSOFF);
; #pragma unroll
;         for (int ai = 0; ai < 2; ++ai)
; #pragma unroll
;             for (int m = 0; m < 4; ++m) {
;                 const int row = row0 + ai * HALF + m * 16; float sq = 0.f;
; #pragma unroll
;                 for (int bj = 0; bj < 2; ++bj)
; #pragma unroll
;                     for (int n = 0; n < 2; ++n) {
;                         const size_t idx = (size_t)row * ldc + u.pn * BM + bj * HALF + wc * 32 + 8 * fq + 4 * n;
;                         const f32x4 b = *(const f32x4*)(base + idx);
;                         const f32x4 v = b + acc[ai][bj][m][n] * alpha;
;                         *(f32x4*)(out + idx) = v;
;                         if (NORM) { u32x2 w; w.x = pk2(v[0], v[1]); w.y = pk2(v[2], v[3]); *(u32x2*)(xb + idx) = w; sq += (v[0] * v[0] + v[1] * v[1]) + (v[2] * v[2] + v[3] * v[3]); }
;                     }
;                 if (NORM) { sq = xor16_sum(sq); sq = xor32_sum(sq); if (fq == 0) __hip_atomic_fetch_add(ss + row, sq, __ATOMIC_RELAXED, __HIP_MEMORY_SCOPE_AGENT); }
;             }
.LBB0_1208:
	v_lshl_add_u32 v148, s12, 8, v137
	s_lshl_b32 s12, s44, 8
	s_ashr_i32 s13, s12, 31
	v_ashrrev_i32_e32 v149, 31, v148
	v_mov_b32_e32 v147, s13
	v_or_b32_e32 v146, s12, v136
	v_lshlrev_b64 v[154:155], 11, v[148:149]
	v_lshl_add_u64 v[158:159], v[154:155], 0, v[146:147]
	v_lshl_add_u64 v[160:161], v[158:159], 2, s[30:31]
	v_mov_b32_e32 v232, v160
	v_mov_b32_e32 v233, v161
	v_mov_b32_e32 v231, 0
	v_mov_b32_e32 v230, 0x0
	v_lshl_add_u64 v[228:229], v[232:233], 0, v[230:231]
	global_load_dwordx4 v[164:167], v[228:229], off
	global_load_dwordx4 v[168:171], v[228:229], off offset:16
	global_load_dwordx4 v[172:175], v[228:229], off offset:512
	global_load_dwordx4 v[176:179], v[228:229], off offset:528
	v_mov_b32_e32 v230, 0x20000
	v_lshl_add_u64 v[228:229], v[232:233], 0, v[230:231]
	global_load_dwordx4 v[180:183], v[228:229], off
	global_load_dwordx4 v[188:191], v[228:229], off offset:16
	global_load_dwordx4 v[192:195], v[228:229], off offset:512
	global_load_dwordx4 v[196:199], v[228:229], off offset:528
	v_mov_b32_e32 v230, 0x40000
	v_lshl_add_u64 v[228:229], v[232:233], 0, v[230:231]
	global_load_dwordx4 v[200:203], v[228:229], off
	global_load_dwordx4 v[204:207], v[228:229], off offset:16
	global_load_dwordx4 v[208:211], v[228:229], off offset:512
	global_load_dwordx4 v[212:215], v[228:229], off offset:528
	v_mov_b32_e32 v230, 0x60000
	v_lshl_add_u64 v[228:229], v[232:233], 0, v[230:231]
	global_load_dwordx4 v[216:219], v[228:229], off
	global_load_dwordx4 v[220:223], v[228:229], off offset:16
	global_load_dwordx4 v[224:227], v[228:229], off offset:512
	global_load_dwordx4 v[234:237], v[228:229], off offset:528
	s_nop 0
	v_lshlrev_b64 v[158:159], 1, v[158:159]
	v_lshl_add_u64 v[162:163], s[6:7], 0, v[158:159]
	s_nop 0
	s_waitcnt vmcnt(12)
	v_pk_add_f32 v[126:127], v[126:127], v[166:167]
	v_pk_add_f32 v[124:125], v[124:125], v[164:165]
	v_cvt_pk_bf16_f32 v241, v126, v127
	v_cvt_pk_bf16_f32 v240, v124, v125
	global_store_dwordx4 v[160:161], v[124:127], off
	s_nop 0
	s_nop 0
	v_or_b32_e32 v162, 8, v158
	v_mov_b32_e32 v163, v159
	v_lshl_add_u64 v[162:163], s[6:7], 0, v[162:163]
	v_mul_f32_e32 v125, v125, v125
	v_mul_f32_e32 v127, v127, v127
	v_fmac_f32_e32 v125, v124, v124
	v_fmac_f32_e32 v127, v126, v126
	v_add_f32_e32 v124, v125, v127
	s_nop 0
	v_pk_add_f32 v[122:123], v[122:123], v[170:171]
	v_pk_add_f32 v[120:121], v[120:121], v[168:169]
	v_cvt_pk_bf16_f32 v243, v122, v123
	v_cvt_pk_bf16_f32 v242, v120, v121
	global_store_dwordx4 v[160:161], v[120:123], off offset:16
	global_store_dwordx4 v[162:163], v[240:243], off offset:-8
	s_nop 0
	v_or_b32_e32 v162, 0x100, v158
	v_mov_b32_e32 v163, v159
	v_lshl_add_u64 v[162:163], s[6:7], 0, v[162:163]
	v_mul_f32_e32 v121, v121, v121
	v_mul_f32_e32 v123, v123, v123
	v_fmac_f32_e32 v121, v120, v120
	v_fmac_f32_e32 v123, v122, v122
	v_add_f32_e32 v120, v121, v123
	v_add_f32_e32 v120, v124, v120
	v_or_b32_e32 v158, 0x108, v158
	v_lshl_add_u64 v[158:159], s[6:7], 0, v[158:159]
	s_nop 0
	v_pk_add_f32 v[118:119], v[118:119], v[174:175]
	v_pk_add_f32 v[116:117], v[116:117], v[172:173]
	v_cvt_pk_bf16_f32 v241, v118, v119
	v_cvt_pk_bf16_f32 v240, v116, v117
	global_store_dwordx4 v[160:161], v[116:119], off offset:512
	s_nop 0
	s_nop 0
	v_mul_f32_e32 v117, v117, v117
	v_mul_f32_e32 v119, v119, v119
	v_fmac_f32_e32 v117, v116, v116
	v_fmac_f32_e32 v119, v118, v118
	v_add_f32_e32 v116, v117, v119
	v_add_f32_e32 v118, v120, v116
	s_nop 0
	v_pk_add_f32 v[114:115], v[114:115], v[178:179]
	v_pk_add_f32 v[112:113], v[112:113], v[176:177]
	v_mov_b32_e32 v230, 0x100000
	v_lshl_add_u64 v[228:229], v[232:233], 0, v[230:231]
	global_load_dwordx4 v[164:167], v[228:229], off
	global_load_dwordx4 v[168:171], v[228:229], off offset:16
	global_load_dwordx4 v[172:175], v[228:229], off offset:512
	global_load_dwordx4 v[176:179], v[228:229], off offset:528
	global_store_dwordx4 v[160:161], v[112:115], off offset:528
	v_cvt_pk_bf16_f32 v242, v112, v113
	v_cvt_pk_bf16_f32 v243, v114, v115
	v_mul_f32_e32 v113, v113, v113
	v_mul_f32_e32 v115, v115, v115
	v_fmac_f32_e32 v113, v112, v112
	v_fmac_f32_e32 v115, v114, v114
	v_add_f32_e32 v112, v113, v115
	v_add_f32_e32 v112, v118, v112
	v_mov_b32_e32 v113, v112
	s_nop 1
	v_permlane16_swap_b32 v113, v112
	global_store_dwordx4 v[158:159], v[240:243], off offset:-8
	v_add_f32_e32 v112, v113, v112
	v_mov_b32_e32 v113, v112
	s_nop 1
	v_permlane32_swap_b32 v113, v112
	s_and_saveexec_b64 s[12:13], s[2:3]
	s_cbranch_execz .LBB0_1210
	v_lshl_add_u64 v[114:115], v[148:149], 2, s[8:9]
	v_add_f32_e32 v112, v113, v112
	global_atomic_add_f32 v[114:115], v112, off
; __device__ __forceinline__ unsigned pk2(float lo, float hi) { f32x2_t v = {lo, hi}; bf16x2_t b = __builtin_convertvector(v, bf16x2_t); return __builtin_bit_cast(unsigned, b); }
; __device__ __forceinline__ float xor16_sum(float v) { float a = v, b = v; swap16(a, b); return a + b; }
; __device__ __forceinline__ float xor32_sum(float v) { float a = v, b = v; swap32(a, b); return a + b; }
;     __device__ __forceinline__ void operator()(const f32x4 (&acc)[2][2][4][2], const Unit& u, int wr, int wc, int fr, int fq) const {
;         const int row0 = u.pm * BM + wr * 64 + fr; constexpr int ldc = 2048; constexpr float alpha = 0.5f * ALPHA2;
;         bf16_t* const xb = (bf16_t*)(ws + XBOFF); __attribute__((address_space(1))) float* const ss = (__attribute__((address_space(1))) float*)(ws + SSOFF);
; #pragma unroll
;         for (int ai = 0; ai < 2; ++ai)
; #pragma unroll
;             for (int m = 0; m < 4; ++m) {
;                 const int row = row0 + ai * HALF + m * 16; float sq = 0.f;
; #pragma unroll
;                 for (int bj = 0; bj < 2; ++bj)
; #pragma unroll
;                     for (int n = 0; n < 2; ++n) {
;                         const size_t idx = (size_t)row * ldc + u.pn * BM + bj * HALF + wc * 32 + 8 * fq + 4 * n;
;                         const f32x4 b = *(const f32x4*)(base + idx);
;                         const f32x4 v = b + acc[ai][bj][m][n] * alpha;
;                         *(f32x4*)(out + idx) = v;
;                         if (NORM) { u32x2 w; w.x = pk2(v[0], v[1]); w.y = pk2(v[2], v[3]); *(u32x2*)(xb + idx) = w; sq += (v[0] * v[0] + v[1] * v[1]) + (v[2] * v[2] + v[3] * v[3]); }
;                     }
;                 if (NORM) { sq = xor16_sum(sq); sq = xor32_sum(sq); if (fq == 0) __hip_atomic_fetch_add(ss + row, sq, __ATOMIC_RELAXED, __HIP_MEMORY_SCOPE_AGENT); }
;             }
.LBB0_1210:
	s_or_b64 exec, exec, s[12:13]
	v_or_b32_e32 v112, 16, v148
	v_ashrrev_i32_e32 v113, 31, v112
	v_lshlrev_b64 v[114:115], 11, v[112:113]
	v_lshl_add_u64 v[118:119], v[114:115], 0, v[146:147]
	v_lshl_add_u64 v[120:121], v[118:119], 2, s[30:31]
	s_nop 0
	v_lshlrev_b64 v[118:119], 1, v[118:119]
	v_lshl_add_u64 v[122:123], s[6:7], 0, v[118:119]
	s_nop 0
	s_waitcnt vmcnt(18)
	v_pk_add_f32 v[110:111], v[110:111], v[182:183]
	v_pk_add_f32 v[108:109], v[108:109], v[180:181]
	v_cvt_pk_bf16_f32 v241, v110, v111
	v_cvt_pk_bf16_f32 v240, v108, v109
	global_store_dwordx4 v[120:121], v[108:111], off
	s_nop 0
	s_nop 0
	v_or_b32_e32 v122, 8, v118
	v_mov_b32_e32 v123, v119
	v_lshl_add_u64 v[122:123], s[6:7], 0, v[122:123]
	v_mul_f32_e32 v109, v109, v109
	v_mul_f32_e32 v111, v111, v111
	v_fmac_f32_e32 v109, v108, v108
	v_fmac_f32_e32 v111, v110, v110
	v_add_f32_e32 v108, v109, v111
	s_nop 0
	v_pk_add_f32 v[106:107], v[106:107], v[190:191]
	v_pk_add_f32 v[104:105], v[104:105], v[188:189]
	v_cvt_pk_bf16_f32 v243, v106, v107
	v_cvt_pk_bf16_f32 v242, v104, v105
	global_store_dwordx4 v[120:121], v[104:107], off offset:16
	global_store_dwordx4 v[122:123], v[240:243], off offset:-8
	s_nop 0
	v_or_b32_e32 v122, 0x100, v118
	v_mov_b32_e32 v123, v119
	v_lshl_add_u64 v[122:123], s[6:7], 0, v[122:123]
	v_mul_f32_e32 v105, v105, v105
	v_mul_f32_e32 v107, v107, v107
	v_fmac_f32_e32 v105, v104, v104
	v_fmac_f32_e32 v107, v106, v106
	v_add_f32_e32 v104, v105, v107
	v_add_f32_e32 v104, v108, v104
	v_or_b32_e32 v118, 0x108, v118
	v_lshl_add_u64 v[118:119], s[6:7], 0, v[118:119]
	s_nop 0
	v_pk_add_f32 v[102:103], v[102:103], v[194:195]
	v_pk_add_f32 v[100:101], v[100:101], v[192:193]
	v_cvt_pk_bf16_f32 v241, v102, v103
	v_cvt_pk_bf16_f32 v240, v100, v101
	global_store_dwordx4 v[120:121], v[100:103], off offset:512
	s_nop 0
	s_nop 0
	v_mul_f32_e32 v101, v101, v101
	v_mul_f32_e32 v103, v103, v103
	v_fmac_f32_e32 v101, v100, v100
	v_fmac_f32_e32 v103, v102, v102
	v_add_f32_e32 v100, v101, v103
	v_add_f32_e32 v102, v104, v100
	s_nop 0
	v_pk_add_f32 v[98:99], v[98:99], v[198:199]
	v_pk_add_f32 v[96:97], v[96:97], v[196:197]
	v_mov_b32_e32 v230, 0x120000
	v_lshl_add_u64 v[228:229], v[232:233], 0, v[230:231]
	global_load_dwordx4 v[180:183], v[228:229], off
	global_load_dwordx4 v[188:191], v[228:229], off offset:16
	global_load_dwordx4 v[192:195], v[228:229], off offset:512
	global_load_dwordx4 v[196:199], v[228:229], off offset:528
	global_store_dwordx4 v[120:121], v[96:99], off offset:528
	v_cvt_pk_bf16_f32 v242, v96, v97
	v_cvt_pk_bf16_f32 v243, v98, v99
	v_mul_f32_e32 v97, v97, v97
	v_mul_f32_e32 v99, v99, v99
	v_fmac_f32_e32 v97, v96, v96
	v_fmac_f32_e32 v99, v98, v98
	v_add_f32_e32 v96, v97, v99
	v_add_f32_e32 v96, v102, v96
	v_mov_b32_e32 v97, v96
	s_nop 1
	v_permlane16_swap_b32 v96, v97
	global_store_dwordx4 v[118:119], v[240:243], off offset:-8
	v_add_f32_e32 v96, v96, v97
	v_mov_b32_e32 v97, v96
	s_nop 1
	v_permlane32_swap_b32 v96, v97
	s_and_saveexec_b64 s[12:13], s[2:3]
	s_cbranch_execz .LBB0_1212
	v_lshl_add_u64 v[98:99], v[112:113], 2, s[8:9]
	v_add_f32_e32 v96, v96, v97
	global_atomic_add_f32 v[98:99], v96, off
; __device__ __forceinline__ unsigned pk2(float lo, float hi) { f32x2_t v = {lo, hi}; bf16x2_t b = __builtin_convertvector(v, bf16x2_t); return __builtin_bit_cast(unsigned, b); }
; __device__ __forceinline__ float xor16_sum(float v) { float a = v, b = v; swap16(a, b); return a + b; }
; __device__ __forceinline__ float xor32_sum(float v) { float a = v, b = v; swap32(a, b); return a + b; }
;     __device__ __forceinline__ void operator()(const f32x4 (&acc)[2][2][4][2], const Unit& u, int wr, int wc, int fr, int fq) const {
;         const int row0 = u.pm * BM + wr * 64 + fr; constexpr int ldc = 2048; constexpr float alpha = 0.5f * ALPHA2;
;         bf16_t* const xb = (bf16_t*)(ws + XBOFF); __attribute__((address_space(1))) float* const ss = (__attribute__((address_space(1))) float*)(ws + SSOFF);
; #pragma unroll
;         for (int ai = 0; ai < 2; ++ai)
; #pragma unroll
;             for (int m = 0; m < 4; ++m) {
;                 const int row = row0 + ai * HALF + m * 16; float sq = 0.f;
; #pragma unroll
;                 for (int bj = 0; bj < 2; ++bj)
; #pragma unroll
;                     for (int n = 0; n < 2; ++n) {
;                         const size_t idx = (size_t)row * ldc + u.pn * BM + bj * HALF + wc * 32 + 8 * fq + 4 * n;
;                         const f32x4 b = *(const f32x4*)(base + idx);
;                         const f32x4 v = b + acc[ai][bj][m][n] * alpha;
;                         *(f32x4*)(out + idx) = v;
;                         if (NORM) { u32x2 w; w.x = pk2(v[0], v[1]); w.y = pk2(v[2], v[3]); *(u32x2*)(xb + idx) = w; sq += (v[0] * v[0] + v[1] * v[1]) + (v[2] * v[2] + v[3] * v[3]); }
;                     }
;                 if (NORM) { sq = xor16_sum(sq); sq = xor32_sum(sq); if (fq == 0) __hip_atomic_fetch_add(ss + row, sq, __ATOMIC_RELAXED, __HIP_MEMORY_SCOPE_AGENT); }
;             }
.LBB0_1212:
	s_or_b64 exec, exec, s[12:13]
	v_or_b32_e32 v96, 32, v148
	v_ashrrev_i32_e32 v97, 31, v96
	v_lshlrev_b64 v[98:99], 11, v[96:97]
	v_lshl_add_u64 v[102:103], v[98:99], 0, v[146:147]
	v_lshl_add_u64 v[104:105], v[102:103], 2, s[30:31]
	s_nop 0
	v_lshlrev_b64 v[102:103], 1, v[102:103]
	v_lshl_add_u64 v[106:107], s[6:7], 0, v[102:103]
	s_nop 0
	s_waitcnt vmcnt(24)
	v_pk_add_f32 v[94:95], v[94:95], v[202:203]
	v_pk_add_f32 v[92:93], v[92:93], v[200:201]
	v_cvt_pk_bf16_f32 v241, v94, v95
	v_cvt_pk_bf16_f32 v240, v92, v93
	global_store_dwordx4 v[104:105], v[92:95], off
	s_nop 0
	s_nop 0
	v_or_b32_e32 v106, 8, v102
	v_mov_b32_e32 v107, v103
	v_lshl_add_u64 v[106:107], s[6:7], 0, v[106:107]
	v_mul_f32_e32 v93, v93, v93
	v_mul_f32_e32 v95, v95, v95
	v_fmac_f32_e32 v93, v92, v92
	v_fmac_f32_e32 v95, v94, v94
	v_add_f32_e32 v92, v93, v95
	s_nop 0
	v_pk_add_f32 v[90:91], v[90:91], v[206:207]
	v_pk_add_f32 v[88:89], v[88:89], v[204:205]
	v_cvt_pk_bf16_f32 v243, v90, v91
	v_cvt_pk_bf16_f32 v242, v88, v89
	global_store_dwordx4 v[104:105], v[88:91], off offset:16
	global_store_dwordx4 v[106:107], v[240:243], off offset:-8
	s_nop 0
	v_or_b32_e32 v106, 0x100, v102
	v_mov_b32_e32 v107, v103
	v_lshl_add_u64 v[106:107], s[6:7], 0, v[106:107]
	v_mul_f32_e32 v89, v89, v89
	v_mul_f32_e32 v91, v91, v91
	v_fmac_f32_e32 v89, v88, v88
	v_fmac_f32_e32 v91, v90, v90
	v_add_f32_e32 v88, v89, v91
	v_add_f32_e32 v88, v92, v88
	v_or_b32_e32 v102, 0x108, v102
	v_lshl_add_u64 v[102:103], s[6:7], 0, v[102:103]
	s_nop 0
	v_pk_add_f32 v[86:87], v[86:87], v[210:211]
	v_pk_add_f32 v[84:85], v[84:85], v[208:209]
	v_cvt_pk_bf16_f32 v241, v86, v87
	v_cvt_pk_bf16_f32 v240, v84, v85
	global_store_dwordx4 v[104:105], v[84:87], off offset:512
	s_nop 0
	s_nop 0
	v_mul_f32_e32 v85, v85, v85
	v_mul_f32_e32 v87, v87, v87
	v_fmac_f32_e32 v85, v84, v84
	v_fmac_f32_e32 v87, v86, v86
	v_add_f32_e32 v84, v85, v87
	v_add_f32_e32 v86, v88, v84
	s_nop 0
	v_pk_add_f32 v[82:83], v[82:83], v[214:215]
	v_pk_add_f32 v[80:81], v[80:81], v[212:213]
	v_mov_b32_e32 v230, 0x140000
	v_lshl_add_u64 v[228:229], v[232:233], 0, v[230:231]
	global_load_dwordx4 v[200:203], v[228:229], off
	global_load_dwordx4 v[204:207], v[228:229], off offset:16
	global_load_dwordx4 v[208:211], v[228:229], off offset:512
	global_load_dwordx4 v[212:215], v[228:229], off offset:528
	global_store_dwordx4 v[104:105], v[80:83], off offset:528
	v_cvt_pk_bf16_f32 v242, v80, v81
	v_cvt_pk_bf16_f32 v243, v82, v83
	v_mul_f32_e32 v81, v81, v81
	v_mul_f32_e32 v83, v83, v83
	v_fmac_f32_e32 v81, v80, v80
	v_fmac_f32_e32 v83, v82, v82
	v_add_f32_e32 v80, v81, v83
	v_add_f32_e32 v80, v86, v80
	v_mov_b32_e32 v81, v80
	s_nop 1
	v_permlane16_swap_b32 v80, v81
	global_store_dwordx4 v[102:103], v[240:243], off offset:-8
	v_add_f32_e32 v80, v80, v81
	v_mov_b32_e32 v81, v80
	s_nop 1
	v_permlane32_swap_b32 v80, v81
	s_and_saveexec_b64 s[12:13], s[2:3]
	s_cbranch_execz .LBB0_1214
	v_lshl_add_u64 v[82:83], v[96:97], 2, s[8:9]
	v_add_f32_e32 v80, v80, v81
	global_atomic_add_f32 v[82:83], v80, off
.LBB0_1214:
	s_or_b64 exec, exec, s[12:13]
	v_or_b32_e32 v80, 48, v148
	v_ashrrev_i32_e32 v81, 31, v80
	v_lshlrev_b64 v[82:83], 11, v[80:81]
	v_lshl_add_u64 v[86:87], v[82:83], 0, v[146:147]
	v_lshl_add_u64 v[88:89], v[86:87], 2, s[30:31]
	s_nop 0
	v_lshlrev_b64 v[86:87], 1, v[86:87]
	v_lshl_add_u64 v[90:91], s[6:7], 0, v[86:87]
	s_nop 0
	s_waitcnt vmcnt(30)
	v_pk_add_f32 v[78:79], v[78:79], v[218:219]
	v_pk_add_f32 v[76:77], v[76:77], v[216:217]
	v_cvt_pk_bf16_f32 v241, v78, v79
	v_cvt_pk_bf16_f32 v240, v76, v77
	global_store_dwordx4 v[88:89], v[76:79], off
	s_nop 0
	s_nop 0
	v_or_b32_e32 v90, 8, v86
	v_mov_b32_e32 v91, v87
	v_lshl_add_u64 v[90:91], s[6:7], 0, v[90:91]
	v_mul_f32_e32 v77, v77, v77
	v_mul_f32_e32 v79, v79, v79
	v_fmac_f32_e32 v77, v76, v76
	v_fmac_f32_e32 v79, v78, v78
	v_add_f32_e32 v76, v77, v79
	s_nop 0
	v_pk_add_f32 v[74:75], v[74:75], v[222:223]
	v_pk_add_f32 v[72:73], v[72:73], v[220:221]
	v_cvt_pk_bf16_f32 v243, v74, v75
	v_cvt_pk_bf16_f32 v242, v72, v73
	global_store_dwordx4 v[88:89], v[72:75], off offset:16
	global_store_dwordx4 v[90:91], v[240:243], off offset:-8
	s_nop 0
	v_or_b32_e32 v90, 0x100, v86
	v_mov_b32_e32 v91, v87
	v_lshl_add_u64 v[90:91], s[6:7], 0, v[90:91]
	v_mul_f32_e32 v73, v73, v73
	v_mul_f32_e32 v75, v75, v75
	v_fmac_f32_e32 v73, v72, v72
	v_fmac_f32_e32 v75, v74, v74
	v_add_f32_e32 v72, v73, v75
	v_add_f32_e32 v72, v76, v72
	v_or_b32_e32 v86, 0x108, v86
	v_lshl_add_u64 v[86:87], s[6:7], 0, v[86:87]
	s_nop 0
	v_pk_add_f32 v[70:71], v[70:71], v[226:227]
	v_pk_add_f32 v[68:69], v[68:69], v[224:225]
	v_cvt_pk_bf16_f32 v241, v70, v71
	v_cvt_pk_bf16_f32 v240, v68, v69
	global_store_dwordx4 v[88:89], v[68:71], off offset:512
	s_nop 0
	s_nop 0
	v_mul_f32_e32 v69, v69, v69
	v_mul_f32_e32 v71, v71, v71
	v_fmac_f32_e32 v69, v68, v68
	v_fmac_f32_e32 v71, v70, v70
	v_add_f32_e32 v68, v69, v71
	v_add_f32_e32 v70, v72, v68
	s_nop 0
	v_pk_add_f32 v[66:67], v[66:67], v[236:237]
	v_pk_add_f32 v[64:65], v[64:65], v[234:235]
	v_mov_b32_e32 v230, 0x160000
	v_lshl_add_u64 v[228:229], v[232:233], 0, v[230:231]
	global_load_dwordx4 v[216:219], v[228:229], off
	global_load_dwordx4 v[220:223], v[228:229], off offset:16
	global_load_dwordx4 v[224:227], v[228:229], off offset:512
	global_load_dwordx4 v[234:237], v[228:229], off offset:528
	global_store_dwordx4 v[88:89], v[64:67], off offset:528
	v_cvt_pk_bf16_f32 v242, v64, v65
	v_cvt_pk_bf16_f32 v243, v66, v67
	v_mul_f32_e32 v65, v65, v65
	v_mul_f32_e32 v67, v67, v67
	v_fmac_f32_e32 v65, v64, v64
	v_fmac_f32_e32 v67, v66, v66
	v_add_f32_e32 v64, v65, v67
	v_add_f32_e32 v64, v70, v64
	v_mov_b32_e32 v65, v64
	s_nop 1
	v_permlane16_swap_b32 v64, v65
	global_store_dwordx4 v[86:87], v[240:243], off offset:-8
	v_add_f32_e32 v64, v64, v65
	v_mov_b32_e32 v65, v64
	s_nop 1
	v_permlane32_swap_b32 v64, v65
	s_and_saveexec_b64 s[12:13], s[2:3]
	s_cbranch_execz .LBB0_1216
	v_lshl_add_u64 v[66:67], v[80:81], 2, s[8:9]
	v_add_f32_e32 v64, v64, v65
	global_atomic_add_f32 v[66:67], v64, off

; __device__ __forceinline__ unsigned pk2(float lo, float hi) { f32x2_t v = {lo, hi}; bf16x2_t b = __builtin_convertvector(v, bf16x2_t); return __builtin_bit_cast(unsigned, b); }
; __device__ __forceinline__ float xor16_sum(float v) { float a = v, b = v; swap16(a, b); return a + b; }
; __device__ __forceinline__ float xor32_sum(float v) { float a = v, b = v; swap32(a, b); return a + b; }
;     __device__ __forceinline__ void operator()(const f32x4 (&acc)[2][2][4][2], const Unit& u, int wr, int wc, int fr, int fq) const {
;         const int row0 = u.pm * BM + wr * 64 + fr; constexpr int ldc = 2048; constexpr float alpha = 0.5f * ALPHA2;
;         bf16_t* const xb = (bf16_t*)(ws + XBOFF); __attribute__((address_space(1))) float* const ss = (__attribute__((address_space(1))) float*)(ws + SSOFF);
; #pragma unroll
;         for (int ai = 0; ai < 2; ++ai)
; #pragma unroll
;             for (int m = 0; m < 4; ++m) {
;                 const int row = row0 + ai * HALF + m * 16; float sq = 0.f;
; #pragma unroll
;                 for (int bj = 0; bj < 2; ++bj)
; #pragma unroll
;                     for (int n = 0; n < 2; ++n) {
;                         const size_t idx = (size_t)row * ldc + u.pn * BM + bj * HALF + wc * 32 + 8 * fq + 4 * n;
;                         const f32x4 b = *(const f32x4*)(base + idx);
;                         const f32x4 v = b + acc[ai][bj][m][n] * alpha;
;                         *(f32x4*)(out + idx) = v;
;                         if (NORM) { u32x2 w; w.x = pk2(v[0], v[1]); w.y = pk2(v[2], v[3]); *(u32x2*)(xb + idx) = w; sq += (v[0] * v[0] + v[1] * v[1]) + (v[2] * v[2] + v[3] * v[3]); }
;                     }
;                 if (NORM) { sq = xor16_sum(sq); sq = xor32_sum(sq); if (fq == 0) __hip_atomic_fetch_add(ss + row, sq, __ATOMIC_RELAXED, __HIP_MEMORY_SCOPE_AGENT); }
;             }
.LBB0_1605:
	v_lshl_add_u32 v148, s12, 8, v137
	s_lshl_b32 s12, s28, 8
	s_ashr_i32 s13, s12, 31
	v_ashrrev_i32_e32 v149, 31, v148
	v_mov_b32_e32 v147, s13
	v_or_b32_e32 v146, s12, v136
	v_lshlrev_b64 v[154:155], 11, v[148:149]
	v_lshl_add_u64 v[158:159], v[154:155], 0, v[146:147]
	v_lshl_add_u64 v[160:161], v[158:159], 2, s[30:31]
	v_mov_b32_e32 v232, v160
	v_mov_b32_e32 v233, v161
	v_mov_b32_e32 v231, 0
	v_mov_b32_e32 v230, 0x0
	v_lshl_add_u64 v[228:229], v[232:233], 0, v[230:231]
	global_load_dwordx4 v[164:167], v[228:229], off
	global_load_dwordx4 v[168:171], v[228:229], off offset:16
	global_load_dwordx4 v[172:175], v[228:229], off offset:512
	global_load_dwordx4 v[176:179], v[228:229], off offset:528
	v_mov_b32_e32 v230, 0x20000
	v_lshl_add_u64 v[228:229], v[232:233], 0, v[230:231]
	global_load_dwordx4 v[180:183], v[228:229], off
	global_load_dwordx4 v[188:191], v[228:229], off offset:16
	global_load_dwordx4 v[192:195], v[228:229], off offset:512
	global_load_dwordx4 v[196:199], v[228:229], off offset:528
	v_mov_b32_e32 v230, 0x40000
	v_lshl_add_u64 v[228:229], v[232:233], 0, v[230:231]
	global_load_dwordx4 v[200:203], v[228:229], off
	global_load_dwordx4 v[204:207], v[228:229], off offset:16
	global_load_dwordx4 v[208:211], v[228:229], off offset:512
	global_load_dwordx4 v[212:215], v[228:229], off offset:528
	v_mov_b32_e32 v230, 0x60000
	v_lshl_add_u64 v[228:229], v[232:233], 0, v[230:231]
	global_load_dwordx4 v[216:219], v[228:229], off
	global_load_dwordx4 v[220:223], v[228:229], off offset:16
	global_load_dwordx4 v[224:227], v[228:229], off offset:512
	global_load_dwordx4 v[234:237], v[228:229], off offset:528
	s_nop 0
	v_lshlrev_b64 v[158:159], 1, v[158:159]
	v_lshl_add_u64 v[162:163], s[40:41], 0, v[158:159]
	s_nop 0
	s_waitcnt vmcnt(12)
	v_pk_add_f32 v[126:127], v[126:127], v[166:167]
	v_pk_add_f32 v[124:125], v[124:125], v[164:165]
	v_cvt_pk_bf16_f32 v241, v126, v127
	v_cvt_pk_bf16_f32 v240, v124, v125
	global_store_dwordx4 v[160:161], v[124:127], off
	s_nop 0
	s_nop 0
	v_or_b32_e32 v162, 8, v158
	v_mov_b32_e32 v163, v159
	v_lshl_add_u64 v[162:163], s[40:41], 0, v[162:163]
	v_mul_f32_e32 v125, v125, v125
	v_mul_f32_e32 v127, v127, v127
	v_fmac_f32_e32 v125, v124, v124
	v_fmac_f32_e32 v127, v126, v126
	v_add_f32_e32 v124, v125, v127
	s_nop 0
	v_pk_add_f32 v[122:123], v[122:123], v[170:171]
	v_pk_add_f32 v[120:121], v[120:121], v[168:169]
	v_cvt_pk_bf16_f32 v243, v122, v123
	v_cvt_pk_bf16_f32 v242, v120, v121
	global_store_dwordx4 v[160:161], v[120:123], off offset:16
	global_store_dwordx4 v[162:163], v[240:243], off offset:-8
	s_nop 0
	v_or_b32_e32 v162, 0x100, v158
	v_mov_b32_e32 v163, v159
	v_lshl_add_u64 v[162:163], s[40:41], 0, v[162:163]
	v_mul_f32_e32 v121, v121, v121
	v_mul_f32_e32 v123, v123, v123
	v_fmac_f32_e32 v121, v120, v120
	v_fmac_f32_e32 v123, v122, v122
	v_add_f32_e32 v120, v121, v123
	v_add_f32_e32 v120, v124, v120
	v_or_b32_e32 v158, 0x108, v158
	v_lshl_add_u64 v[158:159], s[40:41], 0, v[158:159]
	s_nop 0
	v_pk_add_f32 v[118:119], v[118:119], v[174:175]
	v_pk_add_f32 v[116:117], v[116:117], v[172:173]
	v_cvt_pk_bf16_f32 v241, v118, v119
	v_cvt_pk_bf16_f32 v240, v116, v117
	global_store_dwordx4 v[160:161], v[116:119], off offset:512
	s_nop 0
	s_nop 0
	v_mul_f32_e32 v117, v117, v117
	v_mul_f32_e32 v119, v119, v119
	v_fmac_f32_e32 v117, v116, v116
	v_fmac_f32_e32 v119, v118, v118
	v_add_f32_e32 v116, v117, v119
	v_add_f32_e32 v118, v120, v116
	s_nop 0
	v_pk_add_f32 v[114:115], v[114:115], v[178:179]
	v_pk_add_f32 v[112:113], v[112:113], v[176:177]
	v_mov_b32_e32 v230, 0x100000
	v_lshl_add_u64 v[228:229], v[232:233], 0, v[230:231]
	global_load_dwordx4 v[164:167], v[228:229], off
	global_load_dwordx4 v[168:171], v[228:229], off offset:16
	global_load_dwordx4 v[172:175], v[228:229], off offset:512
	global_load_dwordx4 v[176:179], v[228:229], off offset:528
	global_store_dwordx4 v[160:161], v[112:115], off offset:528
	v_cvt_pk_bf16_f32 v242, v112, v113
	v_cvt_pk_bf16_f32 v243, v114, v115
	v_mul_f32_e32 v113, v113, v113
	v_mul_f32_e32 v115, v115, v115
	v_fmac_f32_e32 v113, v112, v112
	v_fmac_f32_e32 v115, v114, v114
	v_add_f32_e32 v112, v113, v115
	v_add_f32_e32 v112, v118, v112
	v_mov_b32_e32 v113, v112
	s_nop 1
	v_permlane16_swap_b32 v113, v112
	global_store_dwordx4 v[158:159], v[240:243], off offset:-8
	v_add_f32_e32 v112, v113, v112
	v_mov_b32_e32 v113, v112
	s_nop 1
	v_permlane32_swap_b32 v113, v112
	s_and_saveexec_b64 s[12:13], s[2:3]
	s_cbranch_execz .LBB0_1607
	v_lshl_add_u64 v[114:115], v[148:149], 2, s[6:7]
	v_add_f32_e32 v112, v113, v112
	global_atomic_add_f32 v[114:115], v112, off
; __device__ __forceinline__ unsigned pk2(float lo, float hi) { f32x2_t v = {lo, hi}; bf16x2_t b = __builtin_convertvector(v, bf16x2_t); return __builtin_bit_cast(unsigned, b); }
; __device__ __forceinline__ float xor16_sum(float v) { float a = v, b = v; swap16(a, b); return a + b; }
; __device__ __forceinline__ float xor32_sum(float v) { float a = v, b = v; swap32(a, b); return a + b; }
;     __device__ __forceinline__ void operator()(const f32x4 (&acc)[2][2][4][2], const Unit& u, int wr, int wc, int fr, int fq) const {
;         const int row0 = u.pm * BM + wr * 64 + fr; constexpr int ldc = 2048; constexpr float alpha = 0.5f * ALPHA2;
;         bf16_t* const xb = (bf16_t*)(ws + XBOFF); __attribute__((address_space(1))) float* const ss = (__attribute__((address_space(1))) float*)(ws + SSOFF);
; #pragma unroll
;         for (int ai = 0; ai < 2; ++ai)
; #pragma unroll
;             for (int m = 0; m < 4; ++m) {
;                 const int row = row0 + ai * HALF + m * 16; float sq = 0.f;
; #pragma unroll
;                 for (int bj = 0; bj < 2; ++bj)
; #pragma unroll
;                     for (int n = 0; n < 2; ++n) {
;                         const size_t idx = (size_t)row * ldc + u.pn * BM + bj * HALF + wc * 32 + 8 * fq + 4 * n;
;                         const f32x4 b = *(const f32x4*)(base + idx);
;                         const f32x4 v = b + acc[ai][bj][m][n] * alpha;
;                         *(f32x4*)(out + idx) = v;
;                         if (NORM) { u32x2 w; w.x = pk2(v[0], v[1]); w.y = pk2(v[2], v[3]); *(u32x2*)(xb + idx) = w; sq += (v[0] * v[0] + v[1] * v[1]) + (v[2] * v[2] + v[3] * v[3]); }
;                     }
;                 if (NORM) { sq = xor16_sum(sq); sq = xor32_sum(sq); if (fq == 0) __hip_atomic_fetch_add(ss + row, sq, __ATOMIC_RELAXED, __HIP_MEMORY_SCOPE_AGENT); }
;             }
.LBB0_1607:
	s_or_b64 exec, exec, s[12:13]
	v_or_b32_e32 v112, 16, v148
	v_ashrrev_i32_e32 v113, 31, v112
	v_lshlrev_b64 v[114:115], 11, v[112:113]
	v_lshl_add_u64 v[118:119], v[114:115], 0, v[146:147]
	v_lshl_add_u64 v[120:121], v[118:119], 2, s[30:31]
	s_nop 0
	v_lshlrev_b64 v[118:119], 1, v[118:119]
	v_lshl_add_u64 v[122:123], s[40:41], 0, v[118:119]
	s_nop 0
	s_waitcnt vmcnt(18)
	v_pk_add_f32 v[110:111], v[110:111], v[182:183]
	v_pk_add_f32 v[108:109], v[108:109], v[180:181]
	v_cvt_pk_bf16_f32 v241, v110, v111
	v_cvt_pk_bf16_f32 v240, v108, v109
	global_store_dwordx4 v[120:121], v[108:111], off
	s_nop 0
	s_nop 0
	v_or_b32_e32 v122, 8, v118
	v_mov_b32_e32 v123, v119
	v_lshl_add_u64 v[122:123], s[40:41], 0, v[122:123]
	v_mul_f32_e32 v109, v109, v109
	v_mul_f32_e32 v111, v111, v111
	v_fmac_f32_e32 v109, v108, v108
	v_fmac_f32_e32 v111, v110, v110
	v_add_f32_e32 v108, v109, v111
	s_nop 0
	v_pk_add_f32 v[106:107], v[106:107], v[190:191]
	v_pk_add_f32 v[104:105], v[104:105], v[188:189]
	v_cvt_pk_bf16_f32 v243, v106, v107
	v_cvt_pk_bf16_f32 v242, v104, v105
	global_store_dwordx4 v[120:121], v[104:107], off offset:16
	global_store_dwordx4 v[122:123], v[240:243], off offset:-8
	s_nop 0
	v_or_b32_e32 v122, 0x100, v118
	v_mov_b32_e32 v123, v119
	v_lshl_add_u64 v[122:123], s[40:41], 0, v[122:123]
	v_mul_f32_e32 v105, v105, v105
	v_mul_f32_e32 v107, v107, v107
	v_fmac_f32_e32 v105, v104, v104
	v_fmac_f32_e32 v107, v106, v106
	v_add_f32_e32 v104, v105, v107
	v_add_f32_e32 v104, v108, v104
	v_or_b32_e32 v118, 0x108, v118
	v_lshl_add_u64 v[118:119], s[40:41], 0, v[118:119]
	s_nop 0
	v_pk_add_f32 v[102:103], v[102:103], v[194:195]
	v_pk_add_f32 v[100:101], v[100:101], v[192:193]
	v_cvt_pk_bf16_f32 v241, v102, v103
	v_cvt_pk_bf16_f32 v240, v100, v101
	global_store_dwordx4 v[120:121], v[100:103], off offset:512
	s_nop 0
	s_nop 0
	v_mul_f32_e32 v101, v101, v101
	v_mul_f32_e32 v103, v103, v103
	v_fmac_f32_e32 v101, v100, v100
	v_fmac_f32_e32 v103, v102, v102
	v_add_f32_e32 v100, v101, v103
	v_add_f32_e32 v102, v104, v100
	s_nop 0
	v_pk_add_f32 v[98:99], v[98:99], v[198:199]
	v_pk_add_f32 v[96:97], v[96:97], v[196:197]
	v_mov_b32_e32 v230, 0x120000
	v_lshl_add_u64 v[228:229], v[232:233], 0, v[230:231]
	global_load_dwordx4 v[180:183], v[228:229], off
	global_load_dwordx4 v[188:191], v[228:229], off offset:16
	global_load_dwordx4 v[192:195], v[228:229], off offset:512
	global_load_dwordx4 v[196:199], v[228:229], off offset:528
	global_store_dwordx4 v[120:121], v[96:99], off offset:528
	v_cvt_pk_bf16_f32 v242, v96, v97
	v_cvt_pk_bf16_f32 v243, v98, v99
	v_mul_f32_e32 v97, v97, v97
	v_mul_f32_e32 v99, v99, v99
	v_fmac_f32_e32 v97, v96, v96
	v_fmac_f32_e32 v99, v98, v98
	v_add_f32_e32 v96, v97, v99
	v_add_f32_e32 v96, v102, v96
	v_mov_b32_e32 v97, v96
	s_nop 1
	v_permlane16_swap_b32 v96, v97
	global_store_dwordx4 v[118:119], v[240:243], off offset:-8
	v_add_f32_e32 v96, v96, v97
	v_mov_b32_e32 v97, v96
	s_nop 1
	v_permlane32_swap_b32 v96, v97
	s_and_saveexec_b64 s[12:13], s[2:3]
	s_cbranch_execz .LBB0_1609
	v_lshl_add_u64 v[98:99], v[112:113], 2, s[6:7]
	v_add_f32_e32 v96, v96, v97
	global_atomic_add_f32 v[98:99], v96, off
; __device__ __forceinline__ unsigned pk2(float lo, float hi) { f32x2_t v = {lo, hi}; bf16x2_t b = __builtin_convertvector(v, bf16x2_t); return __builtin_bit_cast(unsigned, b); }
; __device__ __forceinline__ float xor16_sum(float v) { float a = v, b = v; swap16(a, b); return a + b; }
; __device__ __forceinline__ float xor32_sum(float v) { float a = v, b = v; swap32(a, b); return a + b; }
;     __device__ __forceinline__ void operator()(const f32x4 (&acc)[2][2][4][2], const Unit& u, int wr, int wc, int fr, int fq) const {
;         const int row0 = u.pm * BM + wr * 64 + fr; constexpr int ldc = 2048; constexpr float alpha = 0.5f * ALPHA2;
;         bf16_t* const xb = (bf16_t*)(ws + XBOFF); __attribute__((address_space(1))) float* const ss = (__attribute__((address_space(1))) float*)(ws + SSOFF);
; #pragma unroll
;         for (int ai = 0; ai < 2; ++ai)
; #pragma unroll
;             for (int m = 0; m < 4; ++m) {
;                 const int row = row0 + ai * HALF + m * 16; float sq = 0.f;
; #pragma unroll
;                 for (int bj = 0; bj < 2; ++bj)
; #pragma unroll
;                     for (int n = 0; n < 2; ++n) {
;                         const size_t idx = (size_t)row * ldc + u.pn * BM + bj * HALF + wc * 32 + 8 * fq + 4 * n;
;                         const f32x4 b = *(const f32x4*)(base + idx);
;                         const f32x4 v = b + acc[ai][bj][m][n] * alpha;
;                         *(f32x4*)(out + idx) = v;
;                         if (NORM) { u32x2 w; w.x = pk2(v[0], v[1]); w.y = pk2(v[2], v[3]); *(u32x2*)(xb + idx) = w; sq += (v[0] * v[0] + v[1] * v[1]) + (v[2] * v[2] + v[3] * v[3]); }
;                     }
;                 if (NORM) { sq = xor16_sum(sq); sq = xor32_sum(sq); if (fq == 0) __hip_atomic_fetch_add(ss + row, sq, __ATOMIC_RELAXED, __HIP_MEMORY_SCOPE_AGENT); }
;             }
.LBB0_1609:
	s_or_b64 exec, exec, s[12:13]
	v_or_b32_e32 v96, 32, v148
	v_ashrrev_i32_e32 v97, 31, v96
	v_lshlrev_b64 v[98:99], 11, v[96:97]
	v_lshl_add_u64 v[102:103], v[98:99], 0, v[146:147]
	v_lshl_add_u64 v[104:105], v[102:103], 2, s[30:31]
	s_nop 0
	v_lshlrev_b64 v[102:103], 1, v[102:103]
	v_lshl_add_u64 v[106:107], s[40:41], 0, v[102:103]
	s_nop 0
	s_waitcnt vmcnt(24)
	v_pk_add_f32 v[94:95], v[94:95], v[202:203]
	v_pk_add_f32 v[92:93], v[92:93], v[200:201]
	v_cvt_pk_bf16_f32 v241, v94, v95
	v_cvt_pk_bf16_f32 v240, v92, v93
	global_store_dwordx4 v[104:105], v[92:95], off
	s_nop 0
	s_nop 0
	v_or_b32_e32 v106, 8, v102
	v_mov_b32_e32 v107, v103
	v_lshl_add_u64 v[106:107], s[40:41], 0, v[106:107]
	v_mul_f32_e32 v93, v93, v93
	v_mul_f32_e32 v95, v95, v95
	v_fmac_f32_e32 v93, v92, v92
	v_fmac_f32_e32 v95, v94, v94
	v_add_f32_e32 v92, v93, v95
	s_nop 0
	v_pk_add_f32 v[90:91], v[90:91], v[206:207]
	v_pk_add_f32 v[88:89], v[88:89], v[204:205]
	v_cvt_pk_bf16_f32 v243, v90, v91
	v_cvt_pk_bf16_f32 v242, v88, v89
	global_store_dwordx4 v[104:105], v[88:91], off offset:16
	global_store_dwordx4 v[106:107], v[240:243], off offset:-8
	s_nop 0
	v_or_b32_e32 v106, 0x100, v102
	v_mov_b32_e32 v107, v103
	v_lshl_add_u64 v[106:107], s[40:41], 0, v[106:107]
	v_mul_f32_e32 v89, v89, v89
	v_mul_f32_e32 v91, v91, v91
	v_fmac_f32_e32 v89, v88, v88
	v_fmac_f32_e32 v91, v90, v90
	v_add_f32_e32 v88, v89, v91
	v_add_f32_e32 v88, v92, v88
	v_or_b32_e32 v102, 0x108, v102
	v_lshl_add_u64 v[102:103], s[40:41], 0, v[102:103]
	s_nop 0
	v_pk_add_f32 v[86:87], v[86:87], v[210:211]
	v_pk_add_f32 v[84:85], v[84:85], v[208:209]
	v_cvt_pk_bf16_f32 v241, v86, v87
	v_cvt_pk_bf16_f32 v240, v84, v85
	global_store_dwordx4 v[104:105], v[84:87], off offset:512
	s_nop 0
	s_nop 0
	v_mul_f32_e32 v85, v85, v85
	v_mul_f32_e32 v87, v87, v87
	v_fmac_f32_e32 v85, v84, v84
	v_fmac_f32_e32 v87, v86, v86
	v_add_f32_e32 v84, v85, v87
	v_add_f32_e32 v86, v88, v84
	s_nop 0
	v_pk_add_f32 v[82:83], v[82:83], v[214:215]
	v_pk_add_f32 v[80:81], v[80:81], v[212:213]
	v_mov_b32_e32 v230, 0x140000
	v_lshl_add_u64 v[228:229], v[232:233], 0, v[230:231]
	global_load_dwordx4 v[200:203], v[228:229], off
	global_load_dwordx4 v[204:207], v[228:229], off offset:16
	global_load_dwordx4 v[208:211], v[228:229], off offset:512
	global_load_dwordx4 v[212:215], v[228:229], off offset:528
	global_store_dwordx4 v[104:105], v[80:83], off offset:528
	v_cvt_pk_bf16_f32 v242, v80, v81
	v_cvt_pk_bf16_f32 v243, v82, v83
	v_mul_f32_e32 v81, v81, v81
	v_mul_f32_e32 v83, v83, v83
	v_fmac_f32_e32 v81, v80, v80
	v_fmac_f32_e32 v83, v82, v82
	v_add_f32_e32 v80, v81, v83
	v_add_f32_e32 v80, v86, v80
	v_mov_b32_e32 v81, v80
	s_nop 1
	v_permlane16_swap_b32 v80, v81
	global_store_dwordx4 v[102:103], v[240:243], off offset:-8
	v_add_f32_e32 v80, v80, v81
	v_mov_b32_e32 v81, v80
	s_nop 1
	v_permlane32_swap_b32 v80, v81
	s_and_saveexec_b64 s[12:13], s[2:3]
	s_cbranch_execz .LBB0_1611
	v_lshl_add_u64 v[82:83], v[96:97], 2, s[6:7]
	v_add_f32_e32 v80, v80, v81
	global_atomic_add_f32 v[82:83], v80, off
.LBB0_1611:
	s_or_b64 exec, exec, s[12:13]
	v_or_b32_e32 v80, 48, v148
	v_ashrrev_i32_e32 v81, 31, v80
	v_lshlrev_b64 v[82:83], 11, v[80:81]
	v_lshl_add_u64 v[86:87], v[82:83], 0, v[146:147]
	v_lshl_add_u64 v[88:89], v[86:87], 2, s[30:31]
	s_nop 0
	v_lshlrev_b64 v[86:87], 1, v[86:87]
	v_lshl_add_u64 v[90:91], s[40:41], 0, v[86:87]
	s_nop 0
	s_waitcnt vmcnt(30)
	v_pk_add_f32 v[78:79], v[78:79], v[218:219]
	v_pk_add_f32 v[76:77], v[76:77], v[216:217]
	v_cvt_pk_bf16_f32 v241, v78, v79
	v_cvt_pk_bf16_f32 v240, v76, v77
	global_store_dwordx4 v[88:89], v[76:79], off
	s_nop 0
	s_nop 0
	v_or_b32_e32 v90, 8, v86
	v_mov_b32_e32 v91, v87
	v_lshl_add_u64 v[90:91], s[40:41], 0, v[90:91]
	v_mul_f32_e32 v77, v77, v77
	v_mul_f32_e32 v79, v79, v79
	v_fmac_f32_e32 v77, v76, v76
	v_fmac_f32_e32 v79, v78, v78
	v_add_f32_e32 v76, v77, v79
	s_nop 0
	v_pk_add_f32 v[74:75], v[74:75], v[222:223]
	v_pk_add_f32 v[72:73], v[72:73], v[220:221]
	v_cvt_pk_bf16_f32 v243, v74, v75
	v_cvt_pk_bf16_f32 v242, v72, v73
	global_store_dwordx4 v[88:89], v[72:75], off offset:16
	global_store_dwordx4 v[90:91], v[240:243], off offset:-8
	s_nop 0
	v_or_b32_e32 v90, 0x100, v86
	v_mov_b32_e32 v91, v87
	v_lshl_add_u64 v[90:91], s[40:41], 0, v[90:91]
	v_mul_f32_e32 v73, v73, v73
	v_mul_f32_e32 v75, v75, v75
	v_fmac_f32_e32 v73, v72, v72
	v_fmac_f32_e32 v75, v74, v74
	v_add_f32_e32 v72, v73, v75
	v_add_f32_e32 v72, v76, v72
	v_or_b32_e32 v86, 0x108, v86
	v_lshl_add_u64 v[86:87], s[40:41], 0, v[86:87]
	s_nop 0
	v_pk_add_f32 v[70:71], v[70:71], v[226:227]
	v_pk_add_f32 v[68:69], v[68:69], v[224:225]
	v_cvt_pk_bf16_f32 v241, v70, v71
	v_cvt_pk_bf16_f32 v240, v68, v69
	global_store_dwordx4 v[88:89], v[68:71], off offset:512
	s_nop 0
	s_nop 0
	v_mul_f32_e32 v69, v69, v69
	v_mul_f32_e32 v71, v71, v71
	v_fmac_f32_e32 v69, v68, v68
	v_fmac_f32_e32 v71, v70, v70
	v_add_f32_e32 v68, v69, v71
	v_add_f32_e32 v70, v72, v68
	s_nop 0
	v_pk_add_f32 v[66:67], v[66:67], v[236:237]
	v_pk_add_f32 v[64:65], v[64:65], v[234:235]
	v_mov_b32_e32 v230, 0x160000
	v_lshl_add_u64 v[228:229], v[232:233], 0, v[230:231]
	global_load_dwordx4 v[216:219], v[228:229], off
	global_load_dwordx4 v[220:223], v[228:229], off offset:16
	global_load_dwordx4 v[224:227], v[228:229], off offset:512
	global_load_dwordx4 v[234:237], v[228:229], off offset:528
	global_store_dwordx4 v[88:89], v[64:67], off offset:528
	v_cvt_pk_bf16_f32 v242, v64, v65
	v_cvt_pk_bf16_f32 v243, v66, v67
	v_mul_f32_e32 v65, v65, v65
	v_mul_f32_e32 v67, v67, v67
	v_fmac_f32_e32 v65, v64, v64
	v_fmac_f32_e32 v67, v66, v66
	v_add_f32_e32 v64, v65, v67
	v_add_f32_e32 v64, v70, v64
	v_mov_b32_e32 v65, v64
	s_nop 1
	v_permlane16_swap_b32 v64, v65
	global_store_dwordx4 v[86:87], v[240:243], off offset:-8
	v_add_f32_e32 v64, v64, v65
	v_mov_b32_e32 v65, v64
	s_nop 1
	v_permlane32_swap_b32 v64, v65
	s_and_saveexec_b64 s[12:13], s[2:3]
	s_cbranch_execz .LBB0_1613
	v_lshl_add_u64 v[66:67], v[80:81], 2, s[6:7]
	v_add_f32_e32 v64, v64, v65
	global_atomic_add_f32 v[66:67], v64, off
